# alo pre-pass: token-shift mixing weights loaded once before the loop instead of every iteration
# baseline (speedup 1.0000x reference)
.LBB0_357:
	s_or_b64 exec, exec, s[6:7]
	s_mov_b64 s[6:7], s[0:1]
	s_waitcnt lgkmcnt(0)
	v_mov_b32_e32 v0, v174
	s_lshl_b32 s3, s2, 9
	s_barrier
	v_writelane_b32 v246, s3, 5
	v_add_u32_e32 v32, s3, v0
	s_mov_b32 s3, 0x88000
	v_cmp_gt_i32_e32 vcc, s3, v32
	s_and_saveexec_b64 s[10:11], vcc
	s_cbranch_execz .LBB0_398
	s_load_dwordx2 s[4:5], s[6:7], 0x128
	s_load_dwordx2 s[12:13], s[6:7], 0x28
	s_load_dwordx2 s[8:9], s[6:7], 0x80
	v_and_b32_e32 v1, 31, v0
	v_mov_b32_e32 v21, 0
	v_lshlrev_b32_e32 v20, 5, v1
	s_waitcnt lgkmcnt(0)
	s_add_u32 s18, s4, 0x2800000
	v_lshl_add_u64 v[2:3], s[8:9], 0, v[20:21]
	s_mov_b64 s[14:15], 0x3000
	v_lshlrev_b32_e32 v20, 4, v1
	s_addc_u32 s19, s5, 0
	v_lshlrev_b32_e32 v0, 3, v1
	v_lshl_add_u64 v[22:23], v[2:3], 0, s[14:15]
	v_lshl_add_u64 v[2:3], s[4:5], 0, v[20:21]
	s_mov_b64 s[4:5], 0xf700000
	s_lshl_b32 s3, s70, 9
	v_cmp_lt_u32_e64 s[6:7], 7, v1
	v_cmp_lt_u32_e64 s[8:9], 15, v1
	v_lshl_add_u64 v[24:25], v[2:3], 0, s[4:5]
	s_mov_b64 s[16:17], 0
	s_movk_i32 s4, 0x2e00
	v_mov_b64_e32 v[26:27], s[18:19]
	v_lshlrev_b32_e32 v28, 1, v0
	v_mov_b32_e32 v29, v21
	s_movk_i32 s5, 0x4000
	v_mov_b32_e32 v33, 0x7ff
	s_movk_i32 s22, 0x3fff
	s_movk_i32 s23, 0x3400
	v_lshlrev_b32_e32 v20, 2, v0
	s_mov_b32 s24, 0x87fff
	global_load_dwordx4 v[36:39], v[22:23], off
	global_load_dwordx4 v[40:43], v[22:23], off offset:16
	s_branch .LBB0_360

.LBB0_366:
	s_or_b64 exec, exec, s[18:19]
	s_waitcnt vmcnt(0)
	v_mov_b32_e32 v16, v36
	v_mov_b32_e32 v17, v37
	v_mov_b32_e32 v18, v38
	v_mov_b32_e32 v19, v39
	v_mov_b32_e32 v8, v40
	v_mov_b32_e32 v9, v41
	v_mov_b32_e32 v10, v42
	v_mov_b32_e32 v11, v43
	v_lshlrev_b32_e32 v34, 16, v0
	v_sub_f32_e32 v12, v12, v34
	v_fmac_f32_e32 v34, v12, v16
	s_and_saveexec_b64 s[18:19], s[6:7]
	s_xor_b64 s[18:19], exec, s[18:19]
	s_cbranch_execz .LBB0_368
	v_mul_f32_e32 v12, 0xbfb8aa3b, v34
	v_exp_f32_e32 v12, v12
	s_nop 0
	v_add_f32_e32 v12, 1.0, v12
	v_rcp_f32_e32 v12, v12
	s_nop 0
	v_cndmask_b32_e64 v12, v34, v12, s[8:9]
